# grid barriers: local waiters poll the top-level generation word directly (no per-XCD relay by the leader)
# speedup vs baseline: 1.0157x; 1.0082x over previous
; __device__ __forceinline__ unsigned xb_ld(unsigned* p)              { return __hip_atomic_load(p, __ATOMIC_RELAXED, __HIP_MEMORY_SCOPE_AGENT); }
; __device__ __forceinline__ unsigned xb_add(unsigned* p, unsigned v) { return __hip_atomic_fetch_add(p, v, __ATOMIC_RELAXED, __HIP_MEMORY_SCOPE_AGENT); }
; #define XB_SPIN(cond, bar) do { unsigned _sp = 0; while (cond) { __builtin_amdgcn_s_sleep(1); \
;     if ((++_sp & 255u) == 0u) { if (xb_ld(&(bar)[XB_TMO])) break; if (_sp > XB_SPIN_CAP) { atomicAdd(&(bar)[XB_TMO], 1u); break; } } } } while (0)
; __device__ __forceinline__ void xcd_barrier(const XcdBarrier& b) {
;     ...
;         const unsigned old = xb_add(&bar[XB_XSUB(b.x)], 1u);
;         const unsigned gen = old / nloc;
;         if (old + 1u == (gen + 1u) * nloc) {
;             __builtin_amdgcn_fence(__ATOMIC_RELEASE, "agent");
;             asm volatile("s_waitcnt vmcnt(0)" ::: "memory");
;             const unsigned og = xb_add(&bar[XB_TOP], 1u);
;             const unsigned tg = og / nx;
;             if (og + 1u == (tg + 1u) * nx) xb_add(&bar[XB_TOPGEN], 1u);
;             else XB_SPIN(xb_ld(&bar[XB_TOPGEN]) == tg, bar);
;             __builtin_amdgcn_fence(__ATOMIC_ACQUIRE, "agent");
;             xb_add(&bar[XB_XGEN(b.x)], 1u);
;             asm volatile("s_waitcnt vmcnt(0)" ::: "memory");
;         } else {
;             XB_SPIN(xb_ld(&bar[XB_XGEN(b.x)]) == gen, bar);
;             __builtin_amdgcn_fence(__ATOMIC_ACQUIRE, "agent");
;             asm volatile("s_waitcnt vmcnt(0)" ::: "memory");
.LBB0_88:
	s_or_b64 exec, exec, s[8:9]
	v_cvt_f32_u32_e32 v4, v2
	s_waitcnt vmcnt(0)
	v_readfirstlane_b32 s6, v3
	v_sub_u32_e32 v3, 0, v2
	v_rcp_iflag_f32_e32 v4, v4
	v_add_u32_e32 v5, s6, v1
	v_mul_f32_e32 v4, 0x4f7ffffe, v4
	v_cvt_u32_f32_e32 v4, v4
	v_mul_lo_u32 v1, v3, v4
	v_mul_hi_u32 v1, v4, v1
	v_add_u32_e32 v1, v4, v1
	v_mul_hi_u32 v1, v5, v1
	v_mul_lo_u32 v3, v1, v2
	v_sub_u32_e32 v3, v5, v3
	v_add_u32_e32 v4, 1, v1
	v_cmp_ge_u32_e32 vcc, v3, v2
	s_nop 1
	v_cndmask_b32_e32 v1, v1, v4, vcc
	v_sub_u32_e32 v4, v3, v2
	v_cndmask_b32_e32 v3, v3, v4, vcc
	v_add_u32_e32 v4, 1, v1
	v_cmp_ge_u32_e32 vcc, v3, v2
	v_add_u32_e32 v3, 1, v5
	s_nop 0
	v_cndmask_b32_e32 v1, v1, v4, vcc
	v_mul_lo_u32 v4, v2, v1
	v_add_u32_e32 v2, v4, v2
	v_cmp_ne_u32_e32 vcc, v3, v2
	s_and_saveexec_b64 s[6:7], vcc
	s_xor_b64 s[6:7], exec, s[6:7]
	s_cbranch_execz .LBB0_102
	s_waitcnt lgkmcnt(0)
	s_add_u32 s12, s96, 0x183500
	s_addc_u32 s13, s97, 0
	v_mov_b32_e32 v0, 0
	buffer_inv sc1
	global_load_dword v0, v0, s[12:13] sc1
	s_waitcnt vmcnt(0)
	v_cmp_eq_u32_e32 vcc, v0, v1
	s_and_saveexec_b64 s[8:9], vcc
	s_cbranch_execz .LBB0_101
	s_add_u32 s10, s96, 0x180200
	s_addc_u32 s11, s97, 0
	s_mov_b32 s24, 1
	s_mov_b64 s[14:15], 0
	v_mov_b32_e32 v0, 0
	s_branch .LBB0_92

; __device__ __forceinline__ unsigned xb_ld(unsigned* p)              { return __hip_atomic_load(p, __ATOMIC_RELAXED, __HIP_MEMORY_SCOPE_AGENT); }
; __device__ __forceinline__ unsigned xb_add(unsigned* p, unsigned v) { return __hip_atomic_fetch_add(p, v, __ATOMIC_RELAXED, __HIP_MEMORY_SCOPE_AGENT); }
; #define XB_SPIN(cond, bar) do { unsigned _sp = 0; while (cond) { __builtin_amdgcn_s_sleep(1); \
;     if ((++_sp & 255u) == 0u) { if (xb_ld(&(bar)[XB_TMO])) break; if (_sp > XB_SPIN_CAP) { atomicAdd(&(bar)[XB_TMO], 1u); break; } } } } while (0)
; __device__ __forceinline__ void xcd_barrier(const XcdBarrier& b) {
;     ...
;         const unsigned old = xb_add(&bar[XB_XSUB(b.x)], 1u);
;         const unsigned gen = old / nloc;
;         if (old + 1u == (gen + 1u) * nloc) {
;             __builtin_amdgcn_fence(__ATOMIC_RELEASE, "agent");
;             asm volatile("s_waitcnt vmcnt(0)" ::: "memory");
;             const unsigned og = xb_add(&bar[XB_TOP], 1u);
;             const unsigned tg = og / nx;
;             if (og + 1u == (tg + 1u) * nx) xb_add(&bar[XB_TOPGEN], 1u);
;             else XB_SPIN(xb_ld(&bar[XB_TOPGEN]) == tg, bar);
;             __builtin_amdgcn_fence(__ATOMIC_ACQUIRE, "agent");
;             xb_add(&bar[XB_XGEN(b.x)], 1u);
;             asm volatile("s_waitcnt vmcnt(0)" ::: "memory");
;         } else {
;             XB_SPIN(xb_ld(&bar[XB_XGEN(b.x)]) == gen, bar);
;             __builtin_amdgcn_fence(__ATOMIC_ACQUIRE, "agent");
;             asm volatile("s_waitcnt vmcnt(0)" ::: "memory");
.LBB0_191:
	s_or_b64 exec, exec, s[6:7]
	v_cvt_f32_u32_e32 v4, v2
	s_waitcnt vmcnt(0)
	v_readfirstlane_b32 s4, v3
	v_sub_u32_e32 v3, 0, v2
	v_rcp_iflag_f32_e32 v4, v4
	v_add_u32_e32 v5, s4, v1
	v_mul_f32_e32 v4, 0x4f7ffffe, v4
	v_cvt_u32_f32_e32 v4, v4
	v_mul_lo_u32 v1, v3, v4
	v_mul_hi_u32 v1, v4, v1
	v_add_u32_e32 v1, v4, v1
	v_mul_hi_u32 v1, v5, v1
	v_mul_lo_u32 v3, v1, v2
	v_sub_u32_e32 v3, v5, v3
	v_add_u32_e32 v4, 1, v1
	v_cmp_ge_u32_e32 vcc, v3, v2
	s_nop 1
	v_cndmask_b32_e32 v1, v1, v4, vcc
	v_sub_u32_e32 v4, v3, v2
	v_cndmask_b32_e32 v3, v3, v4, vcc
	v_add_u32_e32 v4, 1, v1
	v_cmp_ge_u32_e32 vcc, v3, v2
	v_add_u32_e32 v3, 1, v5
	s_nop 0
	v_cndmask_b32_e32 v1, v1, v4, vcc
	v_mul_lo_u32 v4, v2, v1
	v_add_u32_e32 v2, v4, v2
	v_cmp_ne_u32_e32 vcc, v3, v2
	s_and_saveexec_b64 s[4:5], vcc
	s_xor_b64 s[4:5], exec, s[4:5]
	s_cbranch_execz .LBB0_205
	s_waitcnt lgkmcnt(0)
	s_add_u32 s10, s96, 0x183500
	s_addc_u32 s11, s97, 0
	v_mov_b32_e32 v0, 0
	buffer_inv sc1
	global_load_dword v0, v0, s[10:11] sc1
	s_waitcnt vmcnt(0)
	v_cmp_eq_u32_e32 vcc, v0, v1
	s_and_saveexec_b64 s[6:7], vcc
	s_cbranch_execz .LBB0_204
	s_add_u32 s8, s96, 0x180200
	s_addc_u32 s9, s97, 0
	s_mov_b32 s22, 1
	s_mov_b64 s[12:13], 0
	v_mov_b32_e32 v0, 0
	s_branch .LBB0_195

; __device__ __forceinline__ unsigned xb_ld(unsigned* p)              { return __hip_atomic_load(p, __ATOMIC_RELAXED, __HIP_MEMORY_SCOPE_AGENT); }
; __device__ __forceinline__ unsigned xb_add(unsigned* p, unsigned v) { return __hip_atomic_fetch_add(p, v, __ATOMIC_RELAXED, __HIP_MEMORY_SCOPE_AGENT); }
; #define XB_SPIN(cond, bar) do { unsigned _sp = 0; while (cond) { __builtin_amdgcn_s_sleep(1); \
;     if ((++_sp & 255u) == 0u) { if (xb_ld(&(bar)[XB_TMO])) break; if (_sp > XB_SPIN_CAP) { atomicAdd(&(bar)[XB_TMO], 1u); break; } } } } while (0)
; __device__ __forceinline__ void xcd_barrier(const XcdBarrier& b) {
;     ...
;         const unsigned old = xb_add(&bar[XB_XSUB(b.x)], 1u);
;         const unsigned gen = old / nloc;
;         if (old + 1u == (gen + 1u) * nloc) {
;             __builtin_amdgcn_fence(__ATOMIC_RELEASE, "agent");
;             asm volatile("s_waitcnt vmcnt(0)" ::: "memory");
;             const unsigned og = xb_add(&bar[XB_TOP], 1u);
;             const unsigned tg = og / nx;
;             if (og + 1u == (tg + 1u) * nx) xb_add(&bar[XB_TOPGEN], 1u);
;             else XB_SPIN(xb_ld(&bar[XB_TOPGEN]) == tg, bar);
;             __builtin_amdgcn_fence(__ATOMIC_ACQUIRE, "agent");
;             xb_add(&bar[XB_XGEN(b.x)], 1u);
;             asm volatile("s_waitcnt vmcnt(0)" ::: "memory");
;         } else {
;             XB_SPIN(xb_ld(&bar[XB_XGEN(b.x)]) == gen, bar);
;             __builtin_amdgcn_fence(__ATOMIC_ACQUIRE, "agent");
;             asm volatile("s_waitcnt vmcnt(0)" ::: "memory");
.LBB0_458:
	s_or_b64 exec, exec, s[6:7]
	v_cvt_f32_u32_e32 v4, v2
	s_waitcnt vmcnt(0)
	v_readfirstlane_b32 s4, v3
	v_sub_u32_e32 v3, 0, v2
	v_rcp_iflag_f32_e32 v4, v4
	v_add_u32_e32 v5, s4, v1
	v_mul_f32_e32 v4, 0x4f7ffffe, v4
	v_cvt_u32_f32_e32 v4, v4
	v_mul_lo_u32 v1, v3, v4
	v_mul_hi_u32 v1, v4, v1
	v_add_u32_e32 v1, v4, v1
	v_mul_hi_u32 v1, v5, v1
	v_mul_lo_u32 v3, v1, v2
	v_sub_u32_e32 v3, v5, v3
	v_add_u32_e32 v4, 1, v1
	v_cmp_ge_u32_e32 vcc, v3, v2
	s_nop 1
	v_cndmask_b32_e32 v1, v1, v4, vcc
	v_sub_u32_e32 v4, v3, v2
	v_cndmask_b32_e32 v3, v3, v4, vcc
	v_add_u32_e32 v4, 1, v1
	v_cmp_ge_u32_e32 vcc, v3, v2
	v_add_u32_e32 v3, 1, v5
	s_nop 0
	v_cndmask_b32_e32 v1, v1, v4, vcc
	v_mul_lo_u32 v4, v2, v1
	v_add_u32_e32 v2, v4, v2
	v_cmp_ne_u32_e32 vcc, v3, v2
	s_and_saveexec_b64 s[4:5], vcc
	s_xor_b64 s[4:5], exec, s[4:5]
	s_cbranch_execz .LBB0_472
	s_waitcnt lgkmcnt(0)
	s_add_u32 s12, s96, 0x183500
	s_addc_u32 s13, s97, 0
	v_mov_b32_e32 v0, 0
	buffer_inv sc1
	global_load_dword v0, v0, s[12:13] sc1
	s_waitcnt vmcnt(0)
	v_cmp_eq_u32_e32 vcc, v0, v1
	s_and_saveexec_b64 s[6:7], vcc
	s_cbranch_execz .LBB0_471
	s_add_u32 s8, s96, 0x180200
	s_addc_u32 s9, s97, 0
	s_mov_b32 s24, 1
	s_mov_b64 s[14:15], 0
	v_mov_b32_e32 v0, 0
	s_branch .LBB0_462
